# P0 adaLN: silu staging loads de-serialized (32 in flight) + GEMV loop rewritten as rolling 32-row weight ring with double-buffered LDS reads, same math order
# speedup vs baseline: 1.0144x; 1.0144x over previous
.LBB0_42:
	s_and_b64 vcc, exec, s[0:1]
	s_cbranch_vccz .LBB0_25
	s_setprio 0
	s_barrier
	s_and_saveexec_b64 s[0:1], s[4:5]
	s_cbranch_execz .LBB0_46
	s_mov_b64 s[2:3], 0
	v_mov_b64_e32 v[2:3], v[18:19]
	v_mov_b32_e32 v4, v46
	v_mov_b32_e32 v5, v15
	s_mov_b64 s[8:9], 0x400
	global_load_dword v96, v[2:3], off
	v_lshl_add_u64 v[2:3], v[2:3], 0, s[8:9]
	global_load_dword v97, v[2:3], off
	v_lshl_add_u64 v[2:3], v[2:3], 0, s[8:9]
	global_load_dword v98, v[2:3], off
	v_lshl_add_u64 v[2:3], v[2:3], 0, s[8:9]
	global_load_dword v99, v[2:3], off
	v_lshl_add_u64 v[2:3], v[2:3], 0, s[8:9]
	global_load_dword v100, v[2:3], off
	v_lshl_add_u64 v[2:3], v[2:3], 0, s[8:9]
	global_load_dword v101, v[2:3], off
	v_lshl_add_u64 v[2:3], v[2:3], 0, s[8:9]
	global_load_dword v102, v[2:3], off
	v_lshl_add_u64 v[2:3], v[2:3], 0, s[8:9]
	global_load_dword v103, v[2:3], off
	v_lshl_add_u64 v[2:3], v[2:3], 0, s[8:9]
	global_load_dword v104, v[2:3], off
	v_lshl_add_u64 v[2:3], v[2:3], 0, s[8:9]
	global_load_dword v105, v[2:3], off
	v_lshl_add_u64 v[2:3], v[2:3], 0, s[8:9]
	global_load_dword v106, v[2:3], off
	v_lshl_add_u64 v[2:3], v[2:3], 0, s[8:9]
	global_load_dword v107, v[2:3], off
	v_lshl_add_u64 v[2:3], v[2:3], 0, s[8:9]
	global_load_dword v108, v[2:3], off
	v_lshl_add_u64 v[2:3], v[2:3], 0, s[8:9]
	global_load_dword v109, v[2:3], off
	v_lshl_add_u64 v[2:3], v[2:3], 0, s[8:9]
	global_load_dword v110, v[2:3], off
	v_lshl_add_u64 v[2:3], v[2:3], 0, s[8:9]
	global_load_dword v111, v[2:3], off
	v_lshl_add_u64 v[2:3], v[2:3], 0, s[8:9]
	global_load_dword v112, v[2:3], off
	v_lshl_add_u64 v[2:3], v[2:3], 0, s[8:9]
	global_load_dword v113, v[2:3], off
	v_lshl_add_u64 v[2:3], v[2:3], 0, s[8:9]
	global_load_dword v114, v[2:3], off
	v_lshl_add_u64 v[2:3], v[2:3], 0, s[8:9]
	global_load_dword v115, v[2:3], off
	v_lshl_add_u64 v[2:3], v[2:3], 0, s[8:9]
	global_load_dword v116, v[2:3], off
	v_lshl_add_u64 v[2:3], v[2:3], 0, s[8:9]
	global_load_dword v117, v[2:3], off
	v_lshl_add_u64 v[2:3], v[2:3], 0, s[8:9]
	global_load_dword v118, v[2:3], off
	v_lshl_add_u64 v[2:3], v[2:3], 0, s[8:9]
	global_load_dword v119, v[2:3], off
	v_lshl_add_u64 v[2:3], v[2:3], 0, s[8:9]
	global_load_dword v120, v[2:3], off
	v_lshl_add_u64 v[2:3], v[2:3], 0, s[8:9]
	global_load_dword v121, v[2:3], off
	v_lshl_add_u64 v[2:3], v[2:3], 0, s[8:9]
	global_load_dword v122, v[2:3], off
	v_lshl_add_u64 v[2:3], v[2:3], 0, s[8:9]
	global_load_dword v123, v[2:3], off
	v_lshl_add_u64 v[2:3], v[2:3], 0, s[8:9]
	global_load_dword v124, v[2:3], off
	v_lshl_add_u64 v[2:3], v[2:3], 0, s[8:9]
	global_load_dword v125, v[2:3], off
	v_lshl_add_u64 v[2:3], v[2:3], 0, s[8:9]
	global_load_dword v126, v[2:3], off
	v_lshl_add_u64 v[2:3], v[2:3], 0, s[8:9]
	global_load_dword v127, v[2:3], off
	s_waitcnt vmcnt(30)
	v_mul_f32_e32 v6, 0xbfb8aa3b, v96
	v_mul_f32_e32 v7, 0xbfb8aa3b, v97
	v_exp_f32_e32 v6, v6
	v_exp_f32_e32 v7, v7
	s_nop 0
	v_add_f32_e32 v6, 1.0, v6
	v_add_f32_e32 v7, 1.0, v7
	v_rcp_f32_e32 v6, v6
	v_rcp_f32_e32 v7, v7
	s_nop 0
	v_mul_f32_e32 v96, v96, v6
	v_mul_f32_e32 v97, v97, v7
	ds_write_b32 v4, v96
	ds_write_b32 v4, v97 offset:1024
	s_waitcnt vmcnt(28)
	v_mul_f32_e32 v6, 0xbfb8aa3b, v98
	v_mul_f32_e32 v7, 0xbfb8aa3b, v99
	v_exp_f32_e32 v6, v6
	v_exp_f32_e32 v7, v7
	s_nop 0
	v_add_f32_e32 v6, 1.0, v6
	v_add_f32_e32 v7, 1.0, v7
	v_rcp_f32_e32 v6, v6
	v_rcp_f32_e32 v7, v7
	s_nop 0
	v_mul_f32_e32 v98, v98, v6
	v_mul_f32_e32 v99, v99, v7
	ds_write_b32 v4, v98 offset:2048
	ds_write_b32 v4, v99 offset:3072
	s_waitcnt vmcnt(26)
	v_mul_f32_e32 v6, 0xbfb8aa3b, v100
	v_mul_f32_e32 v7, 0xbfb8aa3b, v101
	v_exp_f32_e32 v6, v6
	v_exp_f32_e32 v7, v7
	s_nop 0
	v_add_f32_e32 v6, 1.0, v6
	v_add_f32_e32 v7, 1.0, v7
	v_rcp_f32_e32 v6, v6
	v_rcp_f32_e32 v7, v7
	s_nop 0
	v_mul_f32_e32 v100, v100, v6
	v_mul_f32_e32 v101, v101, v7
	ds_write_b32 v4, v100 offset:4096
	ds_write_b32 v4, v101 offset:5120
	s_waitcnt vmcnt(24)
	v_mul_f32_e32 v6, 0xbfb8aa3b, v102
	v_mul_f32_e32 v7, 0xbfb8aa3b, v103
	v_exp_f32_e32 v6, v6
	v_exp_f32_e32 v7, v7
	s_nop 0
	v_add_f32_e32 v6, 1.0, v6
	v_add_f32_e32 v7, 1.0, v7
	v_rcp_f32_e32 v6, v6
	v_rcp_f32_e32 v7, v7
	s_nop 0
	v_mul_f32_e32 v102, v102, v6
	v_mul_f32_e32 v103, v103, v7
	ds_write_b32 v4, v102 offset:6144
	ds_write_b32 v4, v103 offset:7168
	s_waitcnt vmcnt(22)
	v_mul_f32_e32 v6, 0xbfb8aa3b, v104
	v_mul_f32_e32 v7, 0xbfb8aa3b, v105
	v_exp_f32_e32 v6, v6
	v_exp_f32_e32 v7, v7
	s_nop 0
	v_add_f32_e32 v6, 1.0, v6
	v_add_f32_e32 v7, 1.0, v7
	v_rcp_f32_e32 v6, v6
	v_rcp_f32_e32 v7, v7
	s_nop 0
	v_mul_f32_e32 v104, v104, v6
	v_mul_f32_e32 v105, v105, v7
	ds_write_b32 v4, v104 offset:8192
	ds_write_b32 v4, v105 offset:9216
	s_waitcnt vmcnt(20)
	v_mul_f32_e32 v6, 0xbfb8aa3b, v106
	v_mul_f32_e32 v7, 0xbfb8aa3b, v107
	v_exp_f32_e32 v6, v6
	v_exp_f32_e32 v7, v7
	s_nop 0
	v_add_f32_e32 v6, 1.0, v6
	v_add_f32_e32 v7, 1.0, v7
	v_rcp_f32_e32 v6, v6
	v_rcp_f32_e32 v7, v7
	s_nop 0
	v_mul_f32_e32 v106, v106, v6
	v_mul_f32_e32 v107, v107, v7
	ds_write_b32 v4, v106 offset:10240
	ds_write_b32 v4, v107 offset:11264
	s_waitcnt vmcnt(18)
	v_mul_f32_e32 v6, 0xbfb8aa3b, v108
	v_mul_f32_e32 v7, 0xbfb8aa3b, v109
	v_exp_f32_e32 v6, v6
	v_exp_f32_e32 v7, v7
	s_nop 0
	v_add_f32_e32 v6, 1.0, v6
	v_add_f32_e32 v7, 1.0, v7
	v_rcp_f32_e32 v6, v6
	v_rcp_f32_e32 v7, v7
	s_nop 0
	v_mul_f32_e32 v108, v108, v6
	v_mul_f32_e32 v109, v109, v7
	ds_write_b32 v4, v108 offset:12288
	ds_write_b32 v4, v109 offset:13312
	s_waitcnt vmcnt(16)
	v_mul_f32_e32 v6, 0xbfb8aa3b, v110
	v_mul_f32_e32 v7, 0xbfb8aa3b, v111
	v_exp_f32_e32 v6, v6
	v_exp_f32_e32 v7, v7
	s_nop 0
	v_add_f32_e32 v6, 1.0, v6
	v_add_f32_e32 v7, 1.0, v7
	v_rcp_f32_e32 v6, v6
	v_rcp_f32_e32 v7, v7
	s_nop 0
	v_mul_f32_e32 v110, v110, v6
	v_mul_f32_e32 v111, v111, v7
	ds_write_b32 v4, v110 offset:14336
	ds_write_b32 v4, v111 offset:15360
	s_waitcnt vmcnt(14)
	v_mul_f32_e32 v6, 0xbfb8aa3b, v112
	v_mul_f32_e32 v7, 0xbfb8aa3b, v113
	v_exp_f32_e32 v6, v6
	v_exp_f32_e32 v7, v7
	s_nop 0
	v_add_f32_e32 v6, 1.0, v6
	v_add_f32_e32 v7, 1.0, v7
	v_rcp_f32_e32 v6, v6
	v_rcp_f32_e32 v7, v7
	s_nop 0
	v_mul_f32_e32 v112, v112, v6
	v_mul_f32_e32 v113, v113, v7
	ds_write_b32 v4, v112 offset:16384
	ds_write_b32 v4, v113 offset:17408
	s_waitcnt vmcnt(12)
	v_mul_f32_e32 v6, 0xbfb8aa3b, v114
	v_mul_f32_e32 v7, 0xbfb8aa3b, v115
	v_exp_f32_e32 v6, v6
	v_exp_f32_e32 v7, v7
	s_nop 0
	v_add_f32_e32 v6, 1.0, v6
	v_add_f32_e32 v7, 1.0, v7
	v_rcp_f32_e32 v6, v6
	v_rcp_f32_e32 v7, v7
	s_nop 0
	v_mul_f32_e32 v114, v114, v6
	v_mul_f32_e32 v115, v115, v7
	ds_write_b32 v4, v114 offset:18432
	ds_write_b32 v4, v115 offset:19456
	s_waitcnt vmcnt(10)
	v_mul_f32_e32 v6, 0xbfb8aa3b, v116
	v_mul_f32_e32 v7, 0xbfb8aa3b, v117
	v_exp_f32_e32 v6, v6
	v_exp_f32_e32 v7, v7
	s_nop 0
	v_add_f32_e32 v6, 1.0, v6
	v_add_f32_e32 v7, 1.0, v7
	v_rcp_f32_e32 v6, v6
	v_rcp_f32_e32 v7, v7
	s_nop 0
	v_mul_f32_e32 v116, v116, v6
	v_mul_f32_e32 v117, v117, v7
	ds_write_b32 v4, v116 offset:20480
	ds_write_b32 v4, v117 offset:21504
	s_waitcnt vmcnt(8)
	v_mul_f32_e32 v6, 0xbfb8aa3b, v118
	v_mul_f32_e32 v7, 0xbfb8aa3b, v119
	v_exp_f32_e32 v6, v6
	v_exp_f32_e32 v7, v7
	s_nop 0
	v_add_f32_e32 v6, 1.0, v6
	v_add_f32_e32 v7, 1.0, v7
	v_rcp_f32_e32 v6, v6
	v_rcp_f32_e32 v7, v7
	s_nop 0
	v_mul_f32_e32 v118, v118, v6
	v_mul_f32_e32 v119, v119, v7
	ds_write_b32 v4, v118 offset:22528
	ds_write_b32 v4, v119 offset:23552
	s_waitcnt vmcnt(6)
	v_mul_f32_e32 v6, 0xbfb8aa3b, v120
	v_mul_f32_e32 v7, 0xbfb8aa3b, v121
	v_exp_f32_e32 v6, v6
	v_exp_f32_e32 v7, v7
	s_nop 0
	v_add_f32_e32 v6, 1.0, v6
	v_add_f32_e32 v7, 1.0, v7
	v_rcp_f32_e32 v6, v6
	v_rcp_f32_e32 v7, v7
	s_nop 0
	v_mul_f32_e32 v120, v120, v6
	v_mul_f32_e32 v121, v121, v7
	ds_write_b32 v4, v120 offset:24576
	ds_write_b32 v4, v121 offset:25600
	s_waitcnt vmcnt(4)
	v_mul_f32_e32 v6, 0xbfb8aa3b, v122
	v_mul_f32_e32 v7, 0xbfb8aa3b, v123
	v_exp_f32_e32 v6, v6
	v_exp_f32_e32 v7, v7
	s_nop 0
	v_add_f32_e32 v6, 1.0, v6
	v_add_f32_e32 v7, 1.0, v7
	v_rcp_f32_e32 v6, v6
	v_rcp_f32_e32 v7, v7
	s_nop 0
	v_mul_f32_e32 v122, v122, v6
	v_mul_f32_e32 v123, v123, v7
	ds_write_b32 v4, v122 offset:26624
	ds_write_b32 v4, v123 offset:27648
	s_waitcnt vmcnt(2)
	v_mul_f32_e32 v6, 0xbfb8aa3b, v124
	v_mul_f32_e32 v7, 0xbfb8aa3b, v125
	v_exp_f32_e32 v6, v6
	v_exp_f32_e32 v7, v7
	s_nop 0
	v_add_f32_e32 v6, 1.0, v6
	v_add_f32_e32 v7, 1.0, v7
	v_rcp_f32_e32 v6, v6
	v_rcp_f32_e32 v7, v7
	s_nop 0
	v_mul_f32_e32 v124, v124, v6
	v_mul_f32_e32 v125, v125, v7
	ds_write_b32 v4, v124 offset:28672
	ds_write_b32 v4, v125 offset:29696
	s_waitcnt vmcnt(0)
	v_mul_f32_e32 v6, 0xbfb8aa3b, v126
	v_mul_f32_e32 v7, 0xbfb8aa3b, v127
	v_exp_f32_e32 v6, v6
	v_exp_f32_e32 v7, v7
	s_nop 0
	v_add_f32_e32 v6, 1.0, v6
	v_add_f32_e32 v7, 1.0, v7
	v_rcp_f32_e32 v6, v6
	v_rcp_f32_e32 v7, v7
	s_nop 0
	v_mul_f32_e32 v126, v126, v6
	v_mul_f32_e32 v127, v127, v7
	ds_write_b32 v4, v126 offset:30720
	ds_write_b32 v4, v127 offset:31744
.LBB0_46:
	s_or_b64 exec, exec, s[0:1]
	s_mul_hi_i32 s0, s95, 0x2aaaaaab
	s_lshr_b32 s1, s0, 31
	s_ashr_i32 s2, s0, 3
	s_add_i32 s2, s2, s1
	s_mul_i32 s0, s2, 48
	s_sub_i32 s0, s95, s0
	v_lshl_or_b32 v24, s0, 6, v1
	v_ashrrev_i32_e32 v25, 31, v24
	v_lshlrev_b64 v[2:3], 2, v[24:25]
	v_mad_i64_i32 v[2:3], s[0:1], s2, v55, v[2:3]
	v_mov_b32_e32 v32, 0
	v_lshl_add_u64 v[26:27], v[20:21], 0, v[2:3]
	s_mov_b64 s[8:9], 0
	v_mov_b32_e32 v56, v48
	v_mov_b32_e32 v57, v47
	v_mov_b32_e32 v33, v32
	v_mov_b32_e32 v28, v32
	v_mov_b32_e32 v29, v32
	v_mov_b32_e32 v30, v32
	v_mov_b32_e32 v31, v32
	v_mov_b32_e32 v36, v32
	v_mov_b32_e32 v37, v32
	s_mov_b32 s0, 0xfffa3000
	s_mov_b32 s1, -1
	v_lshl_add_u64 v[26:27], v[26:27], 0, s[0:1]
	s_mov_b64 s[0:1], 0x3000
	global_load_dword v96, v[26:27], off
	v_lshl_add_u64 v[26:27], v[26:27], 0, s[0:1]
	global_load_dword v97, v[26:27], off
	v_lshl_add_u64 v[26:27], v[26:27], 0, s[0:1]
	global_load_dword v98, v[26:27], off
	v_lshl_add_u64 v[26:27], v[26:27], 0, s[0:1]
	global_load_dword v99, v[26:27], off
	v_lshl_add_u64 v[26:27], v[26:27], 0, s[0:1]
	global_load_dword v100, v[26:27], off
	v_lshl_add_u64 v[26:27], v[26:27], 0, s[0:1]
	global_load_dword v101, v[26:27], off
	v_lshl_add_u64 v[26:27], v[26:27], 0, s[0:1]
	global_load_dword v102, v[26:27], off
	v_lshl_add_u64 v[26:27], v[26:27], 0, s[0:1]
	global_load_dword v103, v[26:27], off
	v_lshl_add_u64 v[26:27], v[26:27], 0, s[0:1]
	global_load_dword v104, v[26:27], off
	v_lshl_add_u64 v[26:27], v[26:27], 0, s[0:1]
	global_load_dword v105, v[26:27], off
	v_lshl_add_u64 v[26:27], v[26:27], 0, s[0:1]
	global_load_dword v106, v[26:27], off
	v_lshl_add_u64 v[26:27], v[26:27], 0, s[0:1]
	global_load_dword v107, v[26:27], off
	v_lshl_add_u64 v[26:27], v[26:27], 0, s[0:1]
	global_load_dword v108, v[26:27], off
	v_lshl_add_u64 v[26:27], v[26:27], 0, s[0:1]
	global_load_dword v109, v[26:27], off
	v_lshl_add_u64 v[26:27], v[26:27], 0, s[0:1]
	global_load_dword v110, v[26:27], off
	v_lshl_add_u64 v[26:27], v[26:27], 0, s[0:1]
	global_load_dword v111, v[26:27], off
	v_lshl_add_u64 v[26:27], v[26:27], 0, s[0:1]
	global_load_dword v112, v[26:27], off
	v_lshl_add_u64 v[26:27], v[26:27], 0, s[0:1]
	global_load_dword v113, v[26:27], off
	v_lshl_add_u64 v[26:27], v[26:27], 0, s[0:1]
	global_load_dword v114, v[26:27], off
	v_lshl_add_u64 v[26:27], v[26:27], 0, s[0:1]
	global_load_dword v115, v[26:27], off
	v_lshl_add_u64 v[26:27], v[26:27], 0, s[0:1]
	global_load_dword v116, v[26:27], off
	v_lshl_add_u64 v[26:27], v[26:27], 0, s[0:1]
	global_load_dword v117, v[26:27], off
	v_lshl_add_u64 v[26:27], v[26:27], 0, s[0:1]
	global_load_dword v118, v[26:27], off
	v_lshl_add_u64 v[26:27], v[26:27], 0, s[0:1]
	global_load_dword v119, v[26:27], off
	v_lshl_add_u64 v[26:27], v[26:27], 0, s[0:1]
	global_load_dword v120, v[26:27], off
	v_lshl_add_u64 v[26:27], v[26:27], 0, s[0:1]
	global_load_dword v121, v[26:27], off
	v_lshl_add_u64 v[26:27], v[26:27], 0, s[0:1]
	global_load_dword v122, v[26:27], off
	v_lshl_add_u64 v[26:27], v[26:27], 0, s[0:1]
	global_load_dword v123, v[26:27], off
	v_lshl_add_u64 v[26:27], v[26:27], 0, s[0:1]
	global_load_dword v124, v[26:27], off
	v_lshl_add_u64 v[26:27], v[26:27], 0, s[0:1]
	global_load_dword v125, v[26:27], off
	v_lshl_add_u64 v[26:27], v[26:27], 0, s[0:1]
	global_load_dword v126, v[26:27], off
	v_lshl_add_u64 v[26:27], v[26:27], 0, s[0:1]
	global_load_dword v127, v[26:27], off
	v_lshl_add_u64 v[26:27], v[26:27], 0, s[0:1]
	s_waitcnt lgkmcnt(0)
	s_setprio 0
	s_barrier
	ds_read_b128 v[128:131], v56 offset:0
	ds_read_b128 v[132:135], v56 offset:4096
	ds_read_b128 v[136:139], v56 offset:8192
	ds_read_b128 v[140:143], v56 offset:12288
	ds_read_b128 v[144:147], v56 offset:16384
	ds_read_b128 v[148:151], v56 offset:20480
	ds_read_b128 v[152:155], v56 offset:24576
	ds_read_b128 v[156:159], v56 offset:28672
	s_mov_b32 s3, 7
.Lada_loop:
	ds_read_b128 v[160:163], v56 offset:16
	ds_read_b128 v[164:167], v56 offset:4112
	ds_read_b128 v[168:171], v56 offset:8208
	ds_read_b128 v[172:175], v56 offset:12304
	ds_read_b128 v[176:179], v56 offset:16400
	ds_read_b128 v[180:183], v56 offset:20496
	ds_read_b128 v[184:187], v56 offset:24592
	ds_read_b128 v[188:191], v56 offset:28688
	s_waitcnt vmcnt(28) lgkmcnt(8)
	v_mul_f32_e32 v192, v97, v129
	v_mul_f32_e32 v193, v97, v133
	v_mul_f32_e32 v194, v97, v137
	v_mul_f32_e32 v195, v97, v141
	v_mul_f32_e32 v196, v97, v145
	v_mul_f32_e32 v197, v97, v149
	v_mul_f32_e32 v198, v96, v152
	v_mul_f32_e32 v199, v97, v153
	v_mul_f32_e32 v200, v98, v154
	v_mul_f32_e32 v201, v99, v155
	v_mul_f32_e32 v202, v96, v156
	v_mul_f32_e32 v203, v97, v157
	v_mul_f32_e32 v204, v98, v158
	v_mul_f32_e32 v205, v99, v159
	v_fmac_f32_e32 v192, v96, v128
	v_fmac_f32_e32 v193, v96, v132
	v_fmac_f32_e32 v194, v96, v136
	v_fmac_f32_e32 v195, v96, v140
	v_fmac_f32_e32 v196, v96, v144
	v_fmac_f32_e32 v197, v96, v148
	v_add_f32_e32 v198, v198, v199
	v_add_f32_e32 v202, v202, v203
	v_fmac_f32_e32 v192, v98, v130
	v_fmac_f32_e32 v193, v98, v134
	v_fmac_f32_e32 v194, v98, v138
	v_fmac_f32_e32 v195, v98, v142
	v_fmac_f32_e32 v196, v98, v146
	v_fmac_f32_e32 v197, v98, v150
	v_add_f32_e32 v198, v198, v200
	v_add_f32_e32 v202, v202, v204
	v_fmac_f32_e32 v192, v99, v131
	v_fmac_f32_e32 v193, v99, v135
	v_fmac_f32_e32 v194, v99, v139
	v_fmac_f32_e32 v195, v99, v143
	v_fmac_f32_e32 v196, v99, v147
	v_fmac_f32_e32 v197, v99, v151
	v_add_f32_e32 v198, v198, v201
	v_add_f32_e32 v202, v202, v205
	v_add_f32_e32 v28, v28, v192
	v_add_f32_e32 v29, v29, v193
	v_add_f32_e32 v30, v30, v194
	v_add_f32_e32 v31, v31, v195
	v_add_f32_e32 v36, v36, v196
	v_add_f32_e32 v37, v37, v197
	v_add_f32_e32 v32, v32, v198
	v_add_f32_e32 v33, v33, v202
	global_load_dword v96, v[26:27], off
	v_lshl_add_u64 v[26:27], v[26:27], 0, s[0:1]
	global_load_dword v97, v[26:27], off
	v_lshl_add_u64 v[26:27], v[26:27], 0, s[0:1]
	global_load_dword v98, v[26:27], off
	v_lshl_add_u64 v[26:27], v[26:27], 0, s[0:1]
	global_load_dword v99, v[26:27], off
	v_lshl_add_u64 v[26:27], v[26:27], 0, s[0:1]
	ds_read_b128 v[128:131], v56 offset:32
	ds_read_b128 v[132:135], v56 offset:4128
	ds_read_b128 v[136:139], v56 offset:8224
	ds_read_b128 v[140:143], v56 offset:12320
	ds_read_b128 v[144:147], v56 offset:16416
	ds_read_b128 v[148:151], v56 offset:20512
	ds_read_b128 v[152:155], v56 offset:24608
	ds_read_b128 v[156:159], v56 offset:28704
	s_waitcnt vmcnt(28) lgkmcnt(8)
	v_mul_f32_e32 v192, v101, v161
	v_mul_f32_e32 v193, v101, v165
	v_mul_f32_e32 v194, v101, v169
	v_mul_f32_e32 v195, v101, v173
	v_mul_f32_e32 v196, v101, v177
	v_mul_f32_e32 v197, v101, v181
	v_mul_f32_e32 v198, v100, v184
	v_mul_f32_e32 v199, v101, v185
	v_mul_f32_e32 v200, v102, v186
	v_mul_f32_e32 v201, v103, v187
	v_mul_f32_e32 v202, v100, v188
	v_mul_f32_e32 v203, v101, v189
	v_mul_f32_e32 v204, v102, v190
	v_mul_f32_e32 v205, v103, v191
	v_fmac_f32_e32 v192, v100, v160
	v_fmac_f32_e32 v193, v100, v164
	v_fmac_f32_e32 v194, v100, v168
	v_fmac_f32_e32 v195, v100, v172
	v_fmac_f32_e32 v196, v100, v176
	v_fmac_f32_e32 v197, v100, v180
	v_add_f32_e32 v198, v198, v199
	v_add_f32_e32 v202, v202, v203
	v_fmac_f32_e32 v192, v102, v162
	v_fmac_f32_e32 v193, v102, v166
	v_fmac_f32_e32 v194, v102, v170
	v_fmac_f32_e32 v195, v102, v174
	v_fmac_f32_e32 v196, v102, v178
	v_fmac_f32_e32 v197, v102, v182
	v_add_f32_e32 v198, v198, v200
	v_add_f32_e32 v202, v202, v204
	v_fmac_f32_e32 v192, v103, v163
	v_fmac_f32_e32 v193, v103, v167
	v_fmac_f32_e32 v194, v103, v171
	v_fmac_f32_e32 v195, v103, v175
	v_fmac_f32_e32 v196, v103, v179
	v_fmac_f32_e32 v197, v103, v183
	v_add_f32_e32 v198, v198, v201
	v_add_f32_e32 v202, v202, v205
	v_add_f32_e32 v28, v28, v192
	v_add_f32_e32 v29, v29, v193
	v_add_f32_e32 v30, v30, v194
	v_add_f32_e32 v31, v31, v195
	v_add_f32_e32 v36, v36, v196
	v_add_f32_e32 v37, v37, v197
	v_add_f32_e32 v32, v32, v198
	v_add_f32_e32 v33, v33, v202
	global_load_dword v100, v[26:27], off
	v_lshl_add_u64 v[26:27], v[26:27], 0, s[0:1]
	global_load_dword v101, v[26:27], off
	v_lshl_add_u64 v[26:27], v[26:27], 0, s[0:1]
	global_load_dword v102, v[26:27], off
	v_lshl_add_u64 v[26:27], v[26:27], 0, s[0:1]
	global_load_dword v103, v[26:27], off
	v_lshl_add_u64 v[26:27], v[26:27], 0, s[0:1]
	ds_read_b128 v[160:163], v56 offset:48
	ds_read_b128 v[164:167], v56 offset:4144
	ds_read_b128 v[168:171], v56 offset:8240
	ds_read_b128 v[172:175], v56 offset:12336
	ds_read_b128 v[176:179], v56 offset:16432
	ds_read_b128 v[180:183], v56 offset:20528
	ds_read_b128 v[184:187], v56 offset:24624
	ds_read_b128 v[188:191], v56 offset:28720
	s_waitcnt vmcnt(28) lgkmcnt(8)
	v_mul_f32_e32 v192, v105, v129
	v_mul_f32_e32 v193, v105, v133
	v_mul_f32_e32 v194, v105, v137
	v_mul_f32_e32 v195, v105, v141
	v_mul_f32_e32 v196, v105, v145
	v_mul_f32_e32 v197, v105, v149
	v_mul_f32_e32 v198, v104, v152
	v_mul_f32_e32 v199, v105, v153
	v_mul_f32_e32 v200, v106, v154
	v_mul_f32_e32 v201, v107, v155
	v_mul_f32_e32 v202, v104, v156
	v_mul_f32_e32 v203, v105, v157
	v_mul_f32_e32 v204, v106, v158
	v_mul_f32_e32 v205, v107, v159
	v_fmac_f32_e32 v192, v104, v128
	v_fmac_f32_e32 v193, v104, v132
	v_fmac_f32_e32 v194, v104, v136
	v_fmac_f32_e32 v195, v104, v140
	v_fmac_f32_e32 v196, v104, v144
	v_fmac_f32_e32 v197, v104, v148
	v_add_f32_e32 v198, v198, v199
	v_add_f32_e32 v202, v202, v203
	v_fmac_f32_e32 v192, v106, v130
	v_fmac_f32_e32 v193, v106, v134
	v_fmac_f32_e32 v194, v106, v138
	v_fmac_f32_e32 v195, v106, v142
	v_fmac_f32_e32 v196, v106, v146
	v_fmac_f32_e32 v197, v106, v150
	v_add_f32_e32 v198, v198, v200
	v_add_f32_e32 v202, v202, v204
	v_fmac_f32_e32 v192, v107, v131
	v_fmac_f32_e32 v193, v107, v135
	v_fmac_f32_e32 v194, v107, v139
	v_fmac_f32_e32 v195, v107, v143
	v_fmac_f32_e32 v196, v107, v147
	v_fmac_f32_e32 v197, v107, v151
	v_add_f32_e32 v198, v198, v201
	v_add_f32_e32 v202, v202, v205
	v_add_f32_e32 v28, v28, v192
	v_add_f32_e32 v29, v29, v193
	v_add_f32_e32 v30, v30, v194
	v_add_f32_e32 v31, v31, v195
	v_add_f32_e32 v36, v36, v196
	v_add_f32_e32 v37, v37, v197
	v_add_f32_e32 v32, v32, v198
	v_add_f32_e32 v33, v33, v202
	global_load_dword v104, v[26:27], off
	v_lshl_add_u64 v[26:27], v[26:27], 0, s[0:1]
	global_load_dword v105, v[26:27], off
	v_lshl_add_u64 v[26:27], v[26:27], 0, s[0:1]
	global_load_dword v106, v[26:27], off
	v_lshl_add_u64 v[26:27], v[26:27], 0, s[0:1]
	global_load_dword v107, v[26:27], off
	v_lshl_add_u64 v[26:27], v[26:27], 0, s[0:1]
	ds_read_b128 v[128:131], v56 offset:64
	ds_read_b128 v[132:135], v56 offset:4160
	ds_read_b128 v[136:139], v56 offset:8256
	ds_read_b128 v[140:143], v56 offset:12352
	ds_read_b128 v[144:147], v56 offset:16448
	ds_read_b128 v[148:151], v56 offset:20544
	ds_read_b128 v[152:155], v56 offset:24640
	ds_read_b128 v[156:159], v56 offset:28736
	s_waitcnt vmcnt(28) lgkmcnt(8)
	v_mul_f32_e32 v192, v109, v161
	v_mul_f32_e32 v193, v109, v165
	v_mul_f32_e32 v194, v109, v169
	v_mul_f32_e32 v195, v109, v173
	v_mul_f32_e32 v196, v109, v177
	v_mul_f32_e32 v197, v109, v181
	v_mul_f32_e32 v198, v108, v184
	v_mul_f32_e32 v199, v109, v185
	v_mul_f32_e32 v200, v110, v186
	v_mul_f32_e32 v201, v111, v187
	v_mul_f32_e32 v202, v108, v188
	v_mul_f32_e32 v203, v109, v189
	v_mul_f32_e32 v204, v110, v190
	v_mul_f32_e32 v205, v111, v191
	v_fmac_f32_e32 v192, v108, v160
	v_fmac_f32_e32 v193, v108, v164
	v_fmac_f32_e32 v194, v108, v168
	v_fmac_f32_e32 v195, v108, v172
	v_fmac_f32_e32 v196, v108, v176
	v_fmac_f32_e32 v197, v108, v180
	v_add_f32_e32 v198, v198, v199
	v_add_f32_e32 v202, v202, v203
	v_fmac_f32_e32 v192, v110, v162
	v_fmac_f32_e32 v193, v110, v166
	v_fmac_f32_e32 v194, v110, v170
	v_fmac_f32_e32 v195, v110, v174
	v_fmac_f32_e32 v196, v110, v178
	v_fmac_f32_e32 v197, v110, v182
	v_add_f32_e32 v198, v198, v200
	v_add_f32_e32 v202, v202, v204
	v_fmac_f32_e32 v192, v111, v163
	v_fmac_f32_e32 v193, v111, v167
	v_fmac_f32_e32 v194, v111, v171
	v_fmac_f32_e32 v195, v111, v175
	v_fmac_f32_e32 v196, v111, v179
	v_fmac_f32_e32 v197, v111, v183
	v_add_f32_e32 v198, v198, v201
	v_add_f32_e32 v202, v202, v205
	v_add_f32_e32 v28, v28, v192
	v_add_f32_e32 v29, v29, v193
	v_add_f32_e32 v30, v30, v194
	v_add_f32_e32 v31, v31, v195
	v_add_f32_e32 v36, v36, v196
	v_add_f32_e32 v37, v37, v197
	v_add_f32_e32 v32, v32, v198
	v_add_f32_e32 v33, v33, v202
	global_load_dword v108, v[26:27], off
	v_lshl_add_u64 v[26:27], v[26:27], 0, s[0:1]
	global_load_dword v109, v[26:27], off
	v_lshl_add_u64 v[26:27], v[26:27], 0, s[0:1]
	global_load_dword v110, v[26:27], off
	v_lshl_add_u64 v[26:27], v[26:27], 0, s[0:1]
	global_load_dword v111, v[26:27], off
	v_lshl_add_u64 v[26:27], v[26:27], 0, s[0:1]
	ds_read_b128 v[160:163], v56 offset:80
	ds_read_b128 v[164:167], v56 offset:4176
	ds_read_b128 v[168:171], v56 offset:8272
	ds_read_b128 v[172:175], v56 offset:12368
	ds_read_b128 v[176:179], v56 offset:16464
	ds_read_b128 v[180:183], v56 offset:20560
	ds_read_b128 v[184:187], v56 offset:24656
	ds_read_b128 v[188:191], v56 offset:28752
	s_waitcnt vmcnt(28) lgkmcnt(8)
	v_mul_f32_e32 v192, v113, v129
	v_mul_f32_e32 v193, v113, v133
	v_mul_f32_e32 v194, v113, v137
	v_mul_f32_e32 v195, v113, v141
	v_mul_f32_e32 v196, v113, v145
	v_mul_f32_e32 v197, v113, v149
	v_mul_f32_e32 v198, v112, v152
	v_mul_f32_e32 v199, v113, v153
	v_mul_f32_e32 v200, v114, v154
	v_mul_f32_e32 v201, v115, v155
	v_mul_f32_e32 v202, v112, v156
	v_mul_f32_e32 v203, v113, v157
	v_mul_f32_e32 v204, v114, v158
	v_mul_f32_e32 v205, v115, v159
	v_fmac_f32_e32 v192, v112, v128
	v_fmac_f32_e32 v193, v112, v132
	v_fmac_f32_e32 v194, v112, v136
	v_fmac_f32_e32 v195, v112, v140
	v_fmac_f32_e32 v196, v112, v144
	v_fmac_f32_e32 v197, v112, v148
	v_add_f32_e32 v198, v198, v199
	v_add_f32_e32 v202, v202, v203
	v_fmac_f32_e32 v192, v114, v130
	v_fmac_f32_e32 v193, v114, v134
	v_fmac_f32_e32 v194, v114, v138
	v_fmac_f32_e32 v195, v114, v142
	v_fmac_f32_e32 v196, v114, v146
	v_fmac_f32_e32 v197, v114, v150
	v_add_f32_e32 v198, v198, v200
	v_add_f32_e32 v202, v202, v204
	v_fmac_f32_e32 v192, v115, v131
	v_fmac_f32_e32 v193, v115, v135
	v_fmac_f32_e32 v194, v115, v139
	v_fmac_f32_e32 v195, v115, v143
	v_fmac_f32_e32 v196, v115, v147
	v_fmac_f32_e32 v197, v115, v151
	v_add_f32_e32 v198, v198, v201
	v_add_f32_e32 v202, v202, v205
	v_add_f32_e32 v28, v28, v192
	v_add_f32_e32 v29, v29, v193
	v_add_f32_e32 v30, v30, v194
	v_add_f32_e32 v31, v31, v195
	v_add_f32_e32 v36, v36, v196
	v_add_f32_e32 v37, v37, v197
	v_add_f32_e32 v32, v32, v198
	v_add_f32_e32 v33, v33, v202
	global_load_dword v112, v[26:27], off
	v_lshl_add_u64 v[26:27], v[26:27], 0, s[0:1]
	global_load_dword v113, v[26:27], off
	v_lshl_add_u64 v[26:27], v[26:27], 0, s[0:1]
	global_load_dword v114, v[26:27], off
	v_lshl_add_u64 v[26:27], v[26:27], 0, s[0:1]
	global_load_dword v115, v[26:27], off
	v_lshl_add_u64 v[26:27], v[26:27], 0, s[0:1]
	ds_read_b128 v[128:131], v56 offset:96
	ds_read_b128 v[132:135], v56 offset:4192
	ds_read_b128 v[136:139], v56 offset:8288
	ds_read_b128 v[140:143], v56 offset:12384
	ds_read_b128 v[144:147], v56 offset:16480
	ds_read_b128 v[148:151], v56 offset:20576
	ds_read_b128 v[152:155], v56 offset:24672
	ds_read_b128 v[156:159], v56 offset:28768
	s_waitcnt vmcnt(28) lgkmcnt(8)
	v_mul_f32_e32 v192, v117, v161
	v_mul_f32_e32 v193, v117, v165
	v_mul_f32_e32 v194, v117, v169
	v_mul_f32_e32 v195, v117, v173
	v_mul_f32_e32 v196, v117, v177
	v_mul_f32_e32 v197, v117, v181
	v_mul_f32_e32 v198, v116, v184
	v_mul_f32_e32 v199, v117, v185
	v_mul_f32_e32 v200, v118, v186
	v_mul_f32_e32 v201, v119, v187
	v_mul_f32_e32 v202, v116, v188
	v_mul_f32_e32 v203, v117, v189
	v_mul_f32_e32 v204, v118, v190
	v_mul_f32_e32 v205, v119, v191
	v_fmac_f32_e32 v192, v116, v160
	v_fmac_f32_e32 v193, v116, v164
	v_fmac_f32_e32 v194, v116, v168
	v_fmac_f32_e32 v195, v116, v172
	v_fmac_f32_e32 v196, v116, v176
	v_fmac_f32_e32 v197, v116, v180
	v_add_f32_e32 v198, v198, v199
	v_add_f32_e32 v202, v202, v203
	v_fmac_f32_e32 v192, v118, v162
	v_fmac_f32_e32 v193, v118, v166
	v_fmac_f32_e32 v194, v118, v170
	v_fmac_f32_e32 v195, v118, v174
	v_fmac_f32_e32 v196, v118, v178
	v_fmac_f32_e32 v197, v118, v182
	v_add_f32_e32 v198, v198, v200
	v_add_f32_e32 v202, v202, v204
	v_fmac_f32_e32 v192, v119, v163
	v_fmac_f32_e32 v193, v119, v167
	v_fmac_f32_e32 v194, v119, v171
	v_fmac_f32_e32 v195, v119, v175
	v_fmac_f32_e32 v196, v119, v179
	v_fmac_f32_e32 v197, v119, v183
	v_add_f32_e32 v198, v198, v201
	v_add_f32_e32 v202, v202, v205
	v_add_f32_e32 v28, v28, v192
	v_add_f32_e32 v29, v29, v193
	v_add_f32_e32 v30, v30, v194
	v_add_f32_e32 v31, v31, v195
	v_add_f32_e32 v36, v36, v196
	v_add_f32_e32 v37, v37, v197
	v_add_f32_e32 v32, v32, v198
	v_add_f32_e32 v33, v33, v202
	global_load_dword v116, v[26:27], off
	v_lshl_add_u64 v[26:27], v[26:27], 0, s[0:1]
	global_load_dword v117, v[26:27], off
	v_lshl_add_u64 v[26:27], v[26:27], 0, s[0:1]
	global_load_dword v118, v[26:27], off
	v_lshl_add_u64 v[26:27], v[26:27], 0, s[0:1]
	global_load_dword v119, v[26:27], off
	v_lshl_add_u64 v[26:27], v[26:27], 0, s[0:1]
	ds_read_b128 v[160:163], v56 offset:112
	ds_read_b128 v[164:167], v56 offset:4208
	ds_read_b128 v[168:171], v56 offset:8304
	ds_read_b128 v[172:175], v56 offset:12400
	ds_read_b128 v[176:179], v56 offset:16496
	ds_read_b128 v[180:183], v56 offset:20592
	ds_read_b128 v[184:187], v56 offset:24688
	ds_read_b128 v[188:191], v56 offset:28784
	s_waitcnt vmcnt(28) lgkmcnt(8)
	v_mul_f32_e32 v192, v121, v129
	v_mul_f32_e32 v193, v121, v133
	v_mul_f32_e32 v194, v121, v137
	v_mul_f32_e32 v195, v121, v141
	v_mul_f32_e32 v196, v121, v145
	v_mul_f32_e32 v197, v121, v149
	v_mul_f32_e32 v198, v120, v152
	v_mul_f32_e32 v199, v121, v153
	v_mul_f32_e32 v200, v122, v154
	v_mul_f32_e32 v201, v123, v155
	v_mul_f32_e32 v202, v120, v156
	v_mul_f32_e32 v203, v121, v157
	v_mul_f32_e32 v204, v122, v158
	v_mul_f32_e32 v205, v123, v159
	v_fmac_f32_e32 v192, v120, v128
	v_fmac_f32_e32 v193, v120, v132
	v_fmac_f32_e32 v194, v120, v136
	v_fmac_f32_e32 v195, v120, v140
	v_fmac_f32_e32 v196, v120, v144
	v_fmac_f32_e32 v197, v120, v148
	v_add_f32_e32 v198, v198, v199
	v_add_f32_e32 v202, v202, v203
	v_fmac_f32_e32 v192, v122, v130
	v_fmac_f32_e32 v193, v122, v134
	v_fmac_f32_e32 v194, v122, v138
	v_fmac_f32_e32 v195, v122, v142
	v_fmac_f32_e32 v196, v122, v146
	v_fmac_f32_e32 v197, v122, v150
	v_add_f32_e32 v198, v198, v200
	v_add_f32_e32 v202, v202, v204
	v_fmac_f32_e32 v192, v123, v131
	v_fmac_f32_e32 v193, v123, v135
	v_fmac_f32_e32 v194, v123, v139
	v_fmac_f32_e32 v195, v123, v143
	v_fmac_f32_e32 v196, v123, v147
	v_fmac_f32_e32 v197, v123, v151
	v_add_f32_e32 v198, v198, v201
	v_add_f32_e32 v202, v202, v205
	v_add_f32_e32 v28, v28, v192
	v_add_f32_e32 v29, v29, v193
	v_add_f32_e32 v30, v30, v194
	v_add_f32_e32 v31, v31, v195
	v_add_f32_e32 v36, v36, v196
	v_add_f32_e32 v37, v37, v197
	v_add_f32_e32 v32, v32, v198
	v_add_f32_e32 v33, v33, v202
	global_load_dword v120, v[26:27], off
	v_lshl_add_u64 v[26:27], v[26:27], 0, s[0:1]
	global_load_dword v121, v[26:27], off
	v_lshl_add_u64 v[26:27], v[26:27], 0, s[0:1]
	global_load_dword v122, v[26:27], off
	v_lshl_add_u64 v[26:27], v[26:27], 0, s[0:1]
	global_load_dword v123, v[26:27], off
	v_lshl_add_u64 v[26:27], v[26:27], 0, s[0:1]
	ds_read_b128 v[128:131], v56 offset:128
	ds_read_b128 v[132:135], v56 offset:4224
	ds_read_b128 v[136:139], v56 offset:8320
	ds_read_b128 v[140:143], v56 offset:12416
	ds_read_b128 v[144:147], v56 offset:16512
	ds_read_b128 v[148:151], v56 offset:20608
	ds_read_b128 v[152:155], v56 offset:24704
	ds_read_b128 v[156:159], v56 offset:28800
	s_waitcnt vmcnt(28) lgkmcnt(8)
	v_mul_f32_e32 v192, v125, v161
	v_mul_f32_e32 v193, v125, v165
	v_mul_f32_e32 v194, v125, v169
	v_mul_f32_e32 v195, v125, v173
	v_mul_f32_e32 v196, v125, v177
	v_mul_f32_e32 v197, v125, v181
	v_mul_f32_e32 v198, v124, v184
	v_mul_f32_e32 v199, v125, v185
	v_mul_f32_e32 v200, v126, v186
	v_mul_f32_e32 v201, v127, v187
	v_mul_f32_e32 v202, v124, v188
	v_mul_f32_e32 v203, v125, v189
	v_mul_f32_e32 v204, v126, v190
	v_mul_f32_e32 v205, v127, v191
	v_fmac_f32_e32 v192, v124, v160
	v_fmac_f32_e32 v193, v124, v164
	v_fmac_f32_e32 v194, v124, v168
	v_fmac_f32_e32 v195, v124, v172
	v_fmac_f32_e32 v196, v124, v176
	v_fmac_f32_e32 v197, v124, v180
	v_add_f32_e32 v198, v198, v199
	v_add_f32_e32 v202, v202, v203
	v_fmac_f32_e32 v192, v126, v162
	v_fmac_f32_e32 v193, v126, v166
	v_fmac_f32_e32 v194, v126, v170
	v_fmac_f32_e32 v195, v126, v174
	v_fmac_f32_e32 v196, v126, v178
	v_fmac_f32_e32 v197, v126, v182
	v_add_f32_e32 v198, v198, v200
	v_add_f32_e32 v202, v202, v204
	v_fmac_f32_e32 v192, v127, v163
	v_fmac_f32_e32 v193, v127, v167
	v_fmac_f32_e32 v194, v127, v171
	v_fmac_f32_e32 v195, v127, v175
	v_fmac_f32_e32 v196, v127, v179
	v_fmac_f32_e32 v197, v127, v183
	v_add_f32_e32 v198, v198, v201
	v_add_f32_e32 v202, v202, v205
	v_add_f32_e32 v28, v28, v192
	v_add_f32_e32 v29, v29, v193
	v_add_f32_e32 v30, v30, v194
	v_add_f32_e32 v31, v31, v195
	v_add_f32_e32 v36, v36, v196
	v_add_f32_e32 v37, v37, v197
	v_add_f32_e32 v32, v32, v198
	v_add_f32_e32 v33, v33, v202
	global_load_dword v124, v[26:27], off
	v_lshl_add_u64 v[26:27], v[26:27], 0, s[0:1]
	global_load_dword v125, v[26:27], off
	v_lshl_add_u64 v[26:27], v[26:27], 0, s[0:1]
	global_load_dword v126, v[26:27], off
	v_lshl_add_u64 v[26:27], v[26:27], 0, s[0:1]
	global_load_dword v127, v[26:27], off
	v_lshl_add_u64 v[26:27], v[26:27], 0, s[0:1]
	v_add_u32_e32 v56, 0x80, v56
	s_sub_u32 s3, s3, 1
	s_cmp_lg_u32 s3, 0
	s_cbranch_scc1 .Lada_loop
	ds_read_b128 v[160:163], v56 offset:16
	ds_read_b128 v[164:167], v56 offset:4112
	ds_read_b128 v[168:171], v56 offset:8208
	ds_read_b128 v[172:175], v56 offset:12304
	ds_read_b128 v[176:179], v56 offset:16400
	ds_read_b128 v[180:183], v56 offset:20496
	ds_read_b128 v[184:187], v56 offset:24592
	ds_read_b128 v[188:191], v56 offset:28688
	s_waitcnt vmcnt(28) lgkmcnt(8)
	v_mul_f32_e32 v192, v97, v129
	v_mul_f32_e32 v193, v97, v133
	v_mul_f32_e32 v194, v97, v137
	v_mul_f32_e32 v195, v97, v141
	v_mul_f32_e32 v196, v97, v145
	v_mul_f32_e32 v197, v97, v149
	v_mul_f32_e32 v198, v96, v152
	v_mul_f32_e32 v199, v97, v153
	v_mul_f32_e32 v200, v98, v154
	v_mul_f32_e32 v201, v99, v155
	v_mul_f32_e32 v202, v96, v156
	v_mul_f32_e32 v203, v97, v157
	v_mul_f32_e32 v204, v98, v158
	v_mul_f32_e32 v205, v99, v159
	v_fmac_f32_e32 v192, v96, v128
	v_fmac_f32_e32 v193, v96, v132
	v_fmac_f32_e32 v194, v96, v136
	v_fmac_f32_e32 v195, v96, v140
	v_fmac_f32_e32 v196, v96, v144
	v_fmac_f32_e32 v197, v96, v148
	v_add_f32_e32 v198, v198, v199
	v_add_f32_e32 v202, v202, v203
	v_fmac_f32_e32 v192, v98, v130
	v_fmac_f32_e32 v193, v98, v134
	v_fmac_f32_e32 v194, v98, v138
	v_fmac_f32_e32 v195, v98, v142
	v_fmac_f32_e32 v196, v98, v146
	v_fmac_f32_e32 v197, v98, v150
	v_add_f32_e32 v198, v198, v200
	v_add_f32_e32 v202, v202, v204
	v_fmac_f32_e32 v192, v99, v131
	v_fmac_f32_e32 v193, v99, v135
	v_fmac_f32_e32 v194, v99, v139
	v_fmac_f32_e32 v195, v99, v143
	v_fmac_f32_e32 v196, v99, v147
	v_fmac_f32_e32 v197, v99, v151
	v_add_f32_e32 v198, v198, v201
	v_add_f32_e32 v202, v202, v205
	v_add_f32_e32 v28, v28, v192
	v_add_f32_e32 v29, v29, v193
	v_add_f32_e32 v30, v30, v194
	v_add_f32_e32 v31, v31, v195
	v_add_f32_e32 v36, v36, v196
	v_add_f32_e32 v37, v37, v197
	v_add_f32_e32 v32, v32, v198
	v_add_f32_e32 v33, v33, v202
	ds_read_b128 v[128:131], v56 offset:32
	ds_read_b128 v[132:135], v56 offset:4128
	ds_read_b128 v[136:139], v56 offset:8224
	ds_read_b128 v[140:143], v56 offset:12320
	ds_read_b128 v[144:147], v56 offset:16416
	ds_read_b128 v[148:151], v56 offset:20512
	ds_read_b128 v[152:155], v56 offset:24608
	ds_read_b128 v[156:159], v56 offset:28704
	s_waitcnt vmcnt(24) lgkmcnt(8)
	v_mul_f32_e32 v192, v101, v161
	v_mul_f32_e32 v193, v101, v165
	v_mul_f32_e32 v194, v101, v169
	v_mul_f32_e32 v195, v101, v173
	v_mul_f32_e32 v196, v101, v177
	v_mul_f32_e32 v197, v101, v181
	v_mul_f32_e32 v198, v100, v184
	v_mul_f32_e32 v199, v101, v185
	v_mul_f32_e32 v200, v102, v186
	v_mul_f32_e32 v201, v103, v187
	v_mul_f32_e32 v202, v100, v188
	v_mul_f32_e32 v203, v101, v189
	v_mul_f32_e32 v204, v102, v190
	v_mul_f32_e32 v205, v103, v191
	v_fmac_f32_e32 v192, v100, v160
	v_fmac_f32_e32 v193, v100, v164
	v_fmac_f32_e32 v194, v100, v168
	v_fmac_f32_e32 v195, v100, v172
	v_fmac_f32_e32 v196, v100, v176
	v_fmac_f32_e32 v197, v100, v180
	v_add_f32_e32 v198, v198, v199
	v_add_f32_e32 v202, v202, v203
	v_fmac_f32_e32 v192, v102, v162
	v_fmac_f32_e32 v193, v102, v166
	v_fmac_f32_e32 v194, v102, v170
	v_fmac_f32_e32 v195, v102, v174
	v_fmac_f32_e32 v196, v102, v178
	v_fmac_f32_e32 v197, v102, v182
	v_add_f32_e32 v198, v198, v200
	v_add_f32_e32 v202, v202, v204
	v_fmac_f32_e32 v192, v103, v163
	v_fmac_f32_e32 v193, v103, v167
	v_fmac_f32_e32 v194, v103, v171
	v_fmac_f32_e32 v195, v103, v175
	v_fmac_f32_e32 v196, v103, v179
	v_fmac_f32_e32 v197, v103, v183
	v_add_f32_e32 v198, v198, v201
	v_add_f32_e32 v202, v202, v205
	v_add_f32_e32 v28, v28, v192
	v_add_f32_e32 v29, v29, v193
	v_add_f32_e32 v30, v30, v194
	v_add_f32_e32 v31, v31, v195
	v_add_f32_e32 v36, v36, v196
	v_add_f32_e32 v37, v37, v197
	v_add_f32_e32 v32, v32, v198
	v_add_f32_e32 v33, v33, v202
	ds_read_b128 v[160:163], v56 offset:48
	ds_read_b128 v[164:167], v56 offset:4144
	ds_read_b128 v[168:171], v56 offset:8240
	ds_read_b128 v[172:175], v56 offset:12336
	ds_read_b128 v[176:179], v56 offset:16432
	ds_read_b128 v[180:183], v56 offset:20528
	ds_read_b128 v[184:187], v56 offset:24624
	ds_read_b128 v[188:191], v56 offset:28720
	s_waitcnt vmcnt(20) lgkmcnt(8)
	v_mul_f32_e32 v192, v105, v129
	v_mul_f32_e32 v193, v105, v133
	v_mul_f32_e32 v194, v105, v137
	v_mul_f32_e32 v195, v105, v141
	v_mul_f32_e32 v196, v105, v145
	v_mul_f32_e32 v197, v105, v149
	v_mul_f32_e32 v198, v104, v152
	v_mul_f32_e32 v199, v105, v153
	v_mul_f32_e32 v200, v106, v154
	v_mul_f32_e32 v201, v107, v155
	v_mul_f32_e32 v202, v104, v156
	v_mul_f32_e32 v203, v105, v157
	v_mul_f32_e32 v204, v106, v158
	v_mul_f32_e32 v205, v107, v159
	v_fmac_f32_e32 v192, v104, v128
	v_fmac_f32_e32 v193, v104, v132
	v_fmac_f32_e32 v194, v104, v136
	v_fmac_f32_e32 v195, v104, v140
	v_fmac_f32_e32 v196, v104, v144
	v_fmac_f32_e32 v197, v104, v148
	v_add_f32_e32 v198, v198, v199
	v_add_f32_e32 v202, v202, v203
	v_fmac_f32_e32 v192, v106, v130
	v_fmac_f32_e32 v193, v106, v134
	v_fmac_f32_e32 v194, v106, v138
	v_fmac_f32_e32 v195, v106, v142
	v_fmac_f32_e32 v196, v106, v146
	v_fmac_f32_e32 v197, v106, v150
	v_add_f32_e32 v198, v198, v200
	v_add_f32_e32 v202, v202, v204
	v_fmac_f32_e32 v192, v107, v131
	v_fmac_f32_e32 v193, v107, v135
	v_fmac_f32_e32 v194, v107, v139
	v_fmac_f32_e32 v195, v107, v143
	v_fmac_f32_e32 v196, v107, v147
	v_fmac_f32_e32 v197, v107, v151
	v_add_f32_e32 v198, v198, v201
	v_add_f32_e32 v202, v202, v205
	v_add_f32_e32 v28, v28, v192
	v_add_f32_e32 v29, v29, v193
	v_add_f32_e32 v30, v30, v194
	v_add_f32_e32 v31, v31, v195
	v_add_f32_e32 v36, v36, v196
	v_add_f32_e32 v37, v37, v197
	v_add_f32_e32 v32, v32, v198
	v_add_f32_e32 v33, v33, v202
	ds_read_b128 v[128:131], v56 offset:64
	ds_read_b128 v[132:135], v56 offset:4160
	ds_read_b128 v[136:139], v56 offset:8256
	ds_read_b128 v[140:143], v56 offset:12352
	ds_read_b128 v[144:147], v56 offset:16448
	ds_read_b128 v[148:151], v56 offset:20544
	ds_read_b128 v[152:155], v56 offset:24640
	ds_read_b128 v[156:159], v56 offset:28736
	s_waitcnt vmcnt(16) lgkmcnt(8)
	v_mul_f32_e32 v192, v109, v161
	v_mul_f32_e32 v193, v109, v165
	v_mul_f32_e32 v194, v109, v169
	v_mul_f32_e32 v195, v109, v173
	v_mul_f32_e32 v196, v109, v177
	v_mul_f32_e32 v197, v109, v181
	v_mul_f32_e32 v198, v108, v184
	v_mul_f32_e32 v199, v109, v185
	v_mul_f32_e32 v200, v110, v186
	v_mul_f32_e32 v201, v111, v187
	v_mul_f32_e32 v202, v108, v188
	v_mul_f32_e32 v203, v109, v189
	v_mul_f32_e32 v204, v110, v190
	v_mul_f32_e32 v205, v111, v191
	v_fmac_f32_e32 v192, v108, v160
	v_fmac_f32_e32 v193, v108, v164
	v_fmac_f32_e32 v194, v108, v168
	v_fmac_f32_e32 v195, v108, v172
	v_fmac_f32_e32 v196, v108, v176
	v_fmac_f32_e32 v197, v108, v180
	v_add_f32_e32 v198, v198, v199
	v_add_f32_e32 v202, v202, v203
	v_fmac_f32_e32 v192, v110, v162
	v_fmac_f32_e32 v193, v110, v166
	v_fmac_f32_e32 v194, v110, v170
	v_fmac_f32_e32 v195, v110, v174
	v_fmac_f32_e32 v196, v110, v178
	v_fmac_f32_e32 v197, v110, v182
	v_add_f32_e32 v198, v198, v200
	v_add_f32_e32 v202, v202, v204
	v_fmac_f32_e32 v192, v111, v163
	v_fmac_f32_e32 v193, v111, v167
	v_fmac_f32_e32 v194, v111, v171
	v_fmac_f32_e32 v195, v111, v175
	v_fmac_f32_e32 v196, v111, v179
	v_fmac_f32_e32 v197, v111, v183
	v_add_f32_e32 v198, v198, v201
	v_add_f32_e32 v202, v202, v205
	v_add_f32_e32 v28, v28, v192
	v_add_f32_e32 v29, v29, v193
	v_add_f32_e32 v30, v30, v194
	v_add_f32_e32 v31, v31, v195
	v_add_f32_e32 v36, v36, v196
	v_add_f32_e32 v37, v37, v197
	v_add_f32_e32 v32, v32, v198
	v_add_f32_e32 v33, v33, v202
	ds_read_b128 v[160:163], v56 offset:80
	ds_read_b128 v[164:167], v56 offset:4176
	ds_read_b128 v[168:171], v56 offset:8272
	ds_read_b128 v[172:175], v56 offset:12368
	ds_read_b128 v[176:179], v56 offset:16464
	ds_read_b128 v[180:183], v56 offset:20560
	ds_read_b128 v[184:187], v56 offset:24656
	ds_read_b128 v[188:191], v56 offset:28752
	s_waitcnt vmcnt(12) lgkmcnt(8)
	v_mul_f32_e32 v192, v113, v129
	v_mul_f32_e32 v193, v113, v133
	v_mul_f32_e32 v194, v113, v137
	v_mul_f32_e32 v195, v113, v141
	v_mul_f32_e32 v196, v113, v145
	v_mul_f32_e32 v197, v113, v149
	v_mul_f32_e32 v198, v112, v152
	v_mul_f32_e32 v199, v113, v153
	v_mul_f32_e32 v200, v114, v154
	v_mul_f32_e32 v201, v115, v155
	v_mul_f32_e32 v202, v112, v156
	v_mul_f32_e32 v203, v113, v157
	v_mul_f32_e32 v204, v114, v158
	v_mul_f32_e32 v205, v115, v159
	v_fmac_f32_e32 v192, v112, v128
	v_fmac_f32_e32 v193, v112, v132
	v_fmac_f32_e32 v194, v112, v136
	v_fmac_f32_e32 v195, v112, v140
	v_fmac_f32_e32 v196, v112, v144
	v_fmac_f32_e32 v197, v112, v148
	v_add_f32_e32 v198, v198, v199
	v_add_f32_e32 v202, v202, v203
	v_fmac_f32_e32 v192, v114, v130
	v_fmac_f32_e32 v193, v114, v134
	v_fmac_f32_e32 v194, v114, v138
	v_fmac_f32_e32 v195, v114, v142
	v_fmac_f32_e32 v196, v114, v146
	v_fmac_f32_e32 v197, v114, v150
	v_add_f32_e32 v198, v198, v200
	v_add_f32_e32 v202, v202, v204
	v_fmac_f32_e32 v192, v115, v131
	v_fmac_f32_e32 v193, v115, v135
	v_fmac_f32_e32 v194, v115, v139
	v_fmac_f32_e32 v195, v115, v143
	v_fmac_f32_e32 v196, v115, v147
	v_fmac_f32_e32 v197, v115, v151
	v_add_f32_e32 v198, v198, v201
	v_add_f32_e32 v202, v202, v205
	v_add_f32_e32 v28, v28, v192
	v_add_f32_e32 v29, v29, v193
	v_add_f32_e32 v30, v30, v194
	v_add_f32_e32 v31, v31, v195
	v_add_f32_e32 v36, v36, v196
	v_add_f32_e32 v37, v37, v197
	v_add_f32_e32 v32, v32, v198
	v_add_f32_e32 v33, v33, v202
	ds_read_b128 v[128:131], v56 offset:96
	ds_read_b128 v[132:135], v56 offset:4192
	ds_read_b128 v[136:139], v56 offset:8288
	ds_read_b128 v[140:143], v56 offset:12384
	ds_read_b128 v[144:147], v56 offset:16480
	ds_read_b128 v[148:151], v56 offset:20576
	ds_read_b128 v[152:155], v56 offset:24672
	ds_read_b128 v[156:159], v56 offset:28768
	s_waitcnt vmcnt(8) lgkmcnt(8)
	v_mul_f32_e32 v192, v117, v161
	v_mul_f32_e32 v193, v117, v165
	v_mul_f32_e32 v194, v117, v169
	v_mul_f32_e32 v195, v117, v173
	v_mul_f32_e32 v196, v117, v177
	v_mul_f32_e32 v197, v117, v181
	v_mul_f32_e32 v198, v116, v184
	v_mul_f32_e32 v199, v117, v185
	v_mul_f32_e32 v200, v118, v186
	v_mul_f32_e32 v201, v119, v187
	v_mul_f32_e32 v202, v116, v188
	v_mul_f32_e32 v203, v117, v189
	v_mul_f32_e32 v204, v118, v190
	v_mul_f32_e32 v205, v119, v191
	v_fmac_f32_e32 v192, v116, v160
	v_fmac_f32_e32 v193, v116, v164
	v_fmac_f32_e32 v194, v116, v168
	v_fmac_f32_e32 v195, v116, v172
	v_fmac_f32_e32 v196, v116, v176
	v_fmac_f32_e32 v197, v116, v180
	v_add_f32_e32 v198, v198, v199
	v_add_f32_e32 v202, v202, v203
	v_fmac_f32_e32 v192, v118, v162
	v_fmac_f32_e32 v193, v118, v166
	v_fmac_f32_e32 v194, v118, v170
	v_fmac_f32_e32 v195, v118, v174
	v_fmac_f32_e32 v196, v118, v178
	v_fmac_f32_e32 v197, v118, v182
	v_add_f32_e32 v198, v198, v200
	v_add_f32_e32 v202, v202, v204
	v_fmac_f32_e32 v192, v119, v163
	v_fmac_f32_e32 v193, v119, v167
	v_fmac_f32_e32 v194, v119, v171
	v_fmac_f32_e32 v195, v119, v175
	v_fmac_f32_e32 v196, v119, v179
	v_fmac_f32_e32 v197, v119, v183
	v_add_f32_e32 v198, v198, v201
	v_add_f32_e32 v202, v202, v205
	v_add_f32_e32 v28, v28, v192
	v_add_f32_e32 v29, v29, v193
	v_add_f32_e32 v30, v30, v194
	v_add_f32_e32 v31, v31, v195
	v_add_f32_e32 v36, v36, v196
	v_add_f32_e32 v37, v37, v197
	v_add_f32_e32 v32, v32, v198
	v_add_f32_e32 v33, v33, v202
	ds_read_b128 v[160:163], v56 offset:112
	ds_read_b128 v[164:167], v56 offset:4208
	ds_read_b128 v[168:171], v56 offset:8304
	ds_read_b128 v[172:175], v56 offset:12400
	ds_read_b128 v[176:179], v56 offset:16496
	ds_read_b128 v[180:183], v56 offset:20592
	ds_read_b128 v[184:187], v56 offset:24688
	ds_read_b128 v[188:191], v56 offset:28784
	s_waitcnt vmcnt(4) lgkmcnt(8)
	v_mul_f32_e32 v192, v121, v129
	v_mul_f32_e32 v193, v121, v133
	v_mul_f32_e32 v194, v121, v137
	v_mul_f32_e32 v195, v121, v141
	v_mul_f32_e32 v196, v121, v145
	v_mul_f32_e32 v197, v121, v149
	v_mul_f32_e32 v198, v120, v152
	v_mul_f32_e32 v199, v121, v153
	v_mul_f32_e32 v200, v122, v154
	v_mul_f32_e32 v201, v123, v155
	v_mul_f32_e32 v202, v120, v156
	v_mul_f32_e32 v203, v121, v157
	v_mul_f32_e32 v204, v122, v158
	v_mul_f32_e32 v205, v123, v159
	v_fmac_f32_e32 v192, v120, v128
	v_fmac_f32_e32 v193, v120, v132
	v_fmac_f32_e32 v194, v120, v136
	v_fmac_f32_e32 v195, v120, v140
	v_fmac_f32_e32 v196, v120, v144
	v_fmac_f32_e32 v197, v120, v148
	v_add_f32_e32 v198, v198, v199
	v_add_f32_e32 v202, v202, v203
	v_fmac_f32_e32 v192, v122, v130
	v_fmac_f32_e32 v193, v122, v134
	v_fmac_f32_e32 v194, v122, v138
	v_fmac_f32_e32 v195, v122, v142
	v_fmac_f32_e32 v196, v122, v146
	v_fmac_f32_e32 v197, v122, v150
	v_add_f32_e32 v198, v198, v200
	v_add_f32_e32 v202, v202, v204
	v_fmac_f32_e32 v192, v123, v131
	v_fmac_f32_e32 v193, v123, v135
	v_fmac_f32_e32 v194, v123, v139
	v_fmac_f32_e32 v195, v123, v143
	v_fmac_f32_e32 v196, v123, v147
	v_fmac_f32_e32 v197, v123, v151
	v_add_f32_e32 v198, v198, v201
	v_add_f32_e32 v202, v202, v205
	v_add_f32_e32 v28, v28, v192
	v_add_f32_e32 v29, v29, v193
	v_add_f32_e32 v30, v30, v194
	v_add_f32_e32 v31, v31, v195
	v_add_f32_e32 v36, v36, v196
	v_add_f32_e32 v37, v37, v197
	v_add_f32_e32 v32, v32, v198
	v_add_f32_e32 v33, v33, v202
	s_waitcnt vmcnt(0) lgkmcnt(0)
	v_mul_f32_e32 v192, v125, v161
	v_mul_f32_e32 v193, v125, v165
	v_mul_f32_e32 v194, v125, v169
	v_mul_f32_e32 v195, v125, v173
	v_mul_f32_e32 v196, v125, v177
	v_mul_f32_e32 v197, v125, v181
	v_mul_f32_e32 v198, v124, v184
	v_mul_f32_e32 v199, v125, v185
	v_mul_f32_e32 v200, v126, v186
	v_mul_f32_e32 v201, v127, v187
	v_mul_f32_e32 v202, v124, v188
	v_mul_f32_e32 v203, v125, v189
	v_mul_f32_e32 v204, v126, v190
	v_mul_f32_e32 v205, v127, v191
	v_fmac_f32_e32 v192, v124, v160
	v_fmac_f32_e32 v193, v124, v164
	v_fmac_f32_e32 v194, v124, v168
	v_fmac_f32_e32 v195, v124, v172
	v_fmac_f32_e32 v196, v124, v176
	v_fmac_f32_e32 v197, v124, v180
	v_add_f32_e32 v198, v198, v199
	v_add_f32_e32 v202, v202, v203
	v_fmac_f32_e32 v192, v126, v162
	v_fmac_f32_e32 v193, v126, v166
	v_fmac_f32_e32 v194, v126, v170
	v_fmac_f32_e32 v195, v126, v174
	v_fmac_f32_e32 v196, v126, v178
	v_fmac_f32_e32 v197, v126, v182
	v_add_f32_e32 v198, v198, v200
	v_add_f32_e32 v202, v202, v204
	v_fmac_f32_e32 v192, v127, v163
	v_fmac_f32_e32 v193, v127, v167
	v_fmac_f32_e32 v194, v127, v171
	v_fmac_f32_e32 v195, v127, v175
	v_fmac_f32_e32 v196, v127, v179
	v_fmac_f32_e32 v197, v127, v183
	v_add_f32_e32 v198, v198, v201
	v_add_f32_e32 v202, v202, v205
	v_add_f32_e32 v28, v28, v192
	v_add_f32_e32 v29, v29, v193
	v_add_f32_e32 v30, v30, v194
	v_add_f32_e32 v31, v31, v195
	v_add_f32_e32 v36, v36, v196
	v_add_f32_e32 v37, v37, v197
	v_add_f32_e32 v32, v32, v198
	v_add_f32_e32 v33, v33, v202
	s_or_b64 exec, exec, s[8:9]
	s_setprio 0
	s_barrier
	ds_write2st64_b32 v51, v28, v29 offset1:1
	ds_write2st64_b32 v51, v30, v31 offset0:2 offset1:3
	ds_write2st64_b32 v51, v36, v37 offset0:4 offset1:5
	ds_write2st64_b32 v51, v32, v33 offset0:6 offset1:7
	s_waitcnt lgkmcnt(0)
	s_setprio 0
	s_barrier
	s_and_saveexec_b64 s[0:1], s[6:7]
	s_cbranch_execz .LBB0_24
	s_mul_i32 s3, s2, 0xc00
	v_add_u32_e32 v2, s3, v24
	v_ashrrev_i32_e32 v3, 31, v2
	s_lshl_b32 s8, s2, 3
	v_lshl_add_u64 v[2:3], v[2:3], 2, s[44:45]
	v_lshl_add_u64 v[4:5], v[24:25], 2, s[50:51]
	s_mov_b64 s[2:3], 0
	v_mov_b32_e32 v6, v46
	v_mov_b32_e32 v7, v14
